# LRU item prologue: conv weights/bias loaded with two plain loads per thread in the same round trip as the other prologue loads (replaces hipcc copy loops)
# speedup vs baseline: 1.0403x; 1.0018x over previous
.LBB0_340:
	s_and_b32 s52, s11, 7
	s_lshl_b32 s0, s52, 7
	s_barrier
	v_lshrrev_b32_e32 v200, 7, v76
	v_and_b32_e32 v201, 0x7f, v76
	v_lshl_add_u32 v200, v200, 10, v201
	v_add_lshl_u32 v200, v200, s0, 2
	global_load_dword v202, v200, s[48:49]
	v_min_u32_e32 v201, 0x7f, v76
	v_add_lshl_u32 v201, v201, s0, 2
	global_load_dword v203, v201, s[50:51]
.LBB0_359:
	s_bfe_u32 s25, s11, 0x20003
	s_lshl_b32 s3, s25, 5
	s_or_b32 s1, s0, s3
	v_or_b32_e32 v2, s1, v116
	v_lshlrev_b32_e32 v8, 2, v2
	v_add_u32_e32 v0, s1, v79
	global_load_dword v10, v8, s[60:61]
	v_ashrrev_i32_e32 v1, 31, v0
	v_lshlrev_b64 v[0:1], 8, v[0:1]
	v_lshl_or_b32 v0, v78, 1, v0
	v_lshl_add_u64 v[2:3], s[42:43], 0, v[0:1]
	v_lshl_add_u64 v[4:5], s[44:45], 0, v[0:1]
	global_load_dwordx4 v[0:3], v[2:3], off
	s_nop 0
	global_load_dwordx4 v[4:7], v[4:5], off
	s_lshl_b32 s1, s11, 7
	s_and_b32 s18, s1, 0xfffff000
	s_ashr_i32 s19, s18, 31
	s_lshl_b64 s[22:23], s[18:19], 11
	s_add_u32 s1, s57, s22
	s_addc_u32 s16, s63, s23
	s_lshl_b32 s0, s0, 1
	s_add_u32 s20, s1, s0
	s_addc_u32 s21, s16, 0
	global_load_dword v12, v8, s[54:55]
	global_load_dword v13, v8, s[58:59]
	v_lshl_add_u64 v[8:9], s[20:21], 0, v[82:83]
	v_lshl_add_u64 v[20:21], s[20:21], 0, v[84:85]
	v_lshl_add_u64 v[24:25], s[20:21], 0, v[86:87]
	v_lshl_add_u64 v[28:29], s[20:21], 0, v[88:89]
	v_lshl_add_u64 v[32:33], s[20:21], 0, v[90:91]
	v_lshl_add_u64 v[34:35], s[20:21], 0, v[92:93]
	v_lshl_add_u64 v[36:37], s[20:21], 0, v[94:95]
	v_lshl_add_u64 v[38:39], s[20:21], 0, v[96:97]
	v_lshl_add_u64 v[40:41], s[20:21], 0, v[98:99]
	v_lshl_add_u64 v[42:43], s[20:21], 0, v[100:101]
	global_load_dwordx4 v[16:19], v[8:9], off
	s_nop 0
	global_load_dwordx4 v[20:23], v[20:21], off
	s_nop 0
	global_load_dwordx4 v[24:27], v[24:25], off
	s_nop 0
	global_load_dwordx4 v[28:31], v[28:29], off
	s_nop 0
	global_load_dwordx4 v[48:51], v[32:33], off
	global_load_dwordx4 v[52:55], v[34:35], off
	global_load_dwordx4 v[56:59], v[36:37], off
	global_load_dwordx4 v[60:63], v[38:39], off
	global_load_dwordx4 v[64:67], v[40:41], off
	global_load_dwordx4 v[68:71], v[42:43], off
	v_lshl_add_u64 v[44:45], s[20:21], 0, v[102:103]
	v_add_u32_e32 v14, 0x22a00, v124
	v_add_u32_e32 v15, 0x24a00, v124
	s_add_u32 s1, s65, s22
	s_mov_b32 s24, 0
	s_waitcnt vmcnt(14)
	v_mul_f32_e32 v8, 0xbfb8aa3b, v10
	v_exp_f32_e32 v36, v8
	global_load_dwordx4 v[8:11], v[44:45], off
	s_waitcnt vmcnt(14)
	ds_write_b128 v14, v[0:3]
	s_waitcnt vmcnt(13)
	ds_write_b128 v15, v[4:7]
	v_add_f32_e32 v2, 1.0, v36
	v_add_f32_e32 v3, -1.0, v2
	v_frexp_mant_f32_e32 v4, v2
	v_cvt_f64_f32_e32 v[0:1], v2
	v_sub_f32_e32 v5, v3, v2
	v_frexp_exp_i32_f64_e32 v0, v[0:1]
	v_cmp_gt_f32_e64 s[16:17], s94, v4
	v_sub_f32_e32 v3, v36, v3
	v_add_f32_e32 v1, 1.0, v5
	v_subbrev_co_u32_e64 v0, s[16:17], 0, v0, s[16:17]
	v_add_f32_e32 v1, v3, v1
	v_sub_u32_e32 v3, 0, v0
	v_ldexp_f32 v2, v2, v3
	v_add_f32_e32 v4, -1.0, v2
	v_add_f32_e32 v5, 1.0, v2
	v_ldexp_f32 v1, v1, v3
	v_add_f32_e32 v3, 1.0, v4
	v_add_f32_e32 v6, -1.0, v5
	v_sub_f32_e32 v3, v2, v3
	v_sub_f32_e32 v2, v2, v6
	v_add_f32_e32 v6, v1, v3
	v_add_f32_e32 v1, v1, v2
	v_add_f32_e32 v14, v5, v1
	v_rcp_f32_e32 v15, v14
	v_add_f32_e32 v3, v4, v6
	v_sub_f32_e32 v4, v3, v4
	v_sub_f32_e32 v2, v14, v5
	v_mul_f32_e32 v33, v3, v15
	v_sub_f32_e32 v32, v6, v4
	v_mul_f32_e32 v4, v14, v33
	v_sub_f32_e32 v1, v1, v2
	v_fma_f32 v6, v33, v14, -v4
	v_fmac_f32_e32 v6, v33, v1
	v_add_f32_e32 v2, v4, v6
	v_sub_f32_e32 v5, v3, v2
	v_mov_b32_e32 v7, v2
	v_pk_add_f32 v[2:3], v[2:3], v[4:5] neg_lo:[0,1] neg_hi:[0,1]
	v_cvt_f32_i32_e32 v0, v0
	v_pk_add_f32 v[2:3], v[2:3], v[6:7] neg_lo:[0,1] neg_hi:[0,1]
	v_cmp_neq_f32_e64 s[16:17], s96, v36
	v_add_f32_e32 v3, v32, v3
	v_add_f32_e32 v2, v2, v3
	v_add_f32_e32 v3, v5, v2
	v_mul_f32_e32 v7, v15, v3
	v_mul_f32_e32 v4, v14, v7
	v_sub_f32_e32 v5, v5, v3
	v_add_f32_e32 v34, v33, v7
	v_fma_f32 v6, v7, v14, -v4
	v_add_f32_e32 v32, v2, v5
	v_sub_f32_e32 v2, v34, v33
	v_fmac_f32_e32 v6, v7, v1
	v_sub_f32_e32 v1, v7, v2
	v_add_f32_e32 v2, v4, v6
	v_sub_f32_e32 v5, v3, v2
	v_mov_b32_e32 v7, v2
	v_pk_add_f32 v[2:3], v[2:3], v[4:5] neg_lo:[0,1] neg_hi:[0,1]
	s_waitcnt vmcnt(12)
	v_mul_f32_e32 v108, 0xbfb8aa3b, v12
	v_pk_add_f32 v[2:3], v[2:3], v[6:7] neg_lo:[0,1] neg_hi:[0,1]
	s_waitcnt vmcnt(11)
	v_mul_f32_e32 v110, 0xbfb8aa3b, v13
	v_add_f32_e32 v3, v32, v3
	v_add_f32_e32 v2, v2, v3
	v_add_f32_e32 v2, v5, v2
	v_mul_f32_e32 v2, v15, v2
	v_add_f32_e32 v1, v1, v2
	v_add_f32_e32 v2, v34, v1
	v_mul_f32_e32 v4, v2, v2
	v_sub_f32_e32 v5, v2, v34
	v_fmamk_f32 v6, v4, 0x3e9b6dac, v125
	v_sub_f32_e32 v5, v1, v5
	v_mul_f32_e32 v1, v2, v4
	v_fmaak_f32 v105, v4, v6, 0x3f2aaada
	v_ldexp_f32 v7, v5, 1
	v_pk_mul_f32 v[4:5], v[0:1], v[104:105]
	v_ldexp_f32 v3, v2, 1
	v_fma_f32 v2, v0, s95, -v4
	v_fmac_f32_e32 v2, 0xb102e308, v0
	v_pk_add_f32 v[0:1], v[4:5], v[2:3]
	v_mov_b32_e32 v6, v4
	v_sub_f32_e32 v32, v1, v3
	v_pk_add_f32 v[14:15], v[0:1], v[4:5] neg_lo:[0,1] neg_hi:[0,1]
	v_sub_f32_e32 v4, v5, v32
	v_add_f32_e32 v7, v7, v4
	v_pk_add_f32 v[4:5], v[0:1], v[6:7]
	v_mov_b32_e32 v3, v0
	v_mov_b32_e32 v15, v5
	v_pk_add_f32 v[34:35], v[2:3], v[14:15] neg_lo:[0,1] neg_hi:[0,1]
	v_pk_add_f32 v[2:3], v[2:3], v[14:15]
	v_mov_b32_e32 v32, v5
	v_pk_add_f32 v[14:15], v[2:3], v[0:1] op_sel:[1,0] op_sel_hi:[0,1] neg_lo:[0,1] neg_hi:[0,1]
	v_mov_b32_e32 v33, v3
	v_pk_add_f32 v[4:5], v[4:5], v[14:15] op_sel_hi:[1,0] neg_lo:[0,1] neg_hi:[0,1]
	v_pk_mov_b32 v[14:15], v[0:1], v[14:15] op_sel:[1,0]
	v_mov_b32_e32 v6, v7
	v_pk_add_f32 v[14:15], v[32:33], v[14:15] neg_lo:[0,1] neg_hi:[0,1]
	v_mov_b32_e32 v7, v0
	v_pk_add_f32 v[0:1], v[6:7], v[14:15] neg_lo:[0,1] neg_hi:[0,1]
	v_mov_b32_e32 v4, v34
	v_pk_add_f32 v[4:5], v[4:5], v[0:1]
	v_mov_b32_e32 v35, v3
	v_pk_add_f32 v[6:7], v[4:5], v[4:5] op_sel:[0,1] op_sel_hi:[1,0]
	s_waitcnt vmcnt(10)
	v_cndmask_b32_e64 v33, v17, 0, s[4:5]
	v_pk_add_f32 v[2:3], v[2:3], v[6:7] op_sel:[1,0] op_sel_hi:[0,1]
	v_mov_b32_e32 v5, v2
	v_pk_add_f32 v[14:15], v[4:5], v[34:35] neg_lo:[0,1] neg_hi:[0,1]
	v_mov_b32_e32 v1, v6
	v_sub_f32_e32 v3, v4, v14
	v_pk_add_f32 v[0:1], v[0:1], v[14:15] neg_lo:[0,1] neg_hi:[0,1]
	v_sub_f32_e32 v3, v34, v3
	v_add_f32_e32 v0, v0, v3
	v_add_f32_e32 v0, v0, v1
	v_add_f32_e32 v0, v2, v0
	v_cndmask_b32_e64 v0, v127, v0, s[16:17]
	v_cmp_ngt_f32_e64 s[16:17], -1.0, v36
	v_cndmask_b32_e64 v35, v19, 0, s[4:5]
	v_cndmask_b32_e64 v34, v18, 0, s[4:5]
	v_cndmask_b32_e64 v0, v128, v0, s[16:17]
	v_cmp_neq_f32_e64 s[16:17], -1.0, v36
	v_cndmask_b32_e64 v32, v16, 0, s[4:5]
	s_waitcnt vmcnt(9)
	v_cndmask_b32_e64 v39, v23, 0, s[4:5]
	v_cndmask_b32_e64 v0, v129, v0, s[16:17]
	v_cmp_lt_f32_e64 s[16:17], |v36|, s97
	v_cndmask_b32_e64 v38, v22, 0, s[4:5]
	v_cndmask_b32_e64 v37, v21, 0, s[4:5]
	v_cndmask_b32_e64 v0, v0, v36, s[16:17]
	s_addc_u32 s16, s67, s23
	s_add_u32 s0, s1, s0
	s_addc_u32 s1, s16, 0
	s_lshl_b32 s16, s25, 6
	s_add_u32 s22, s0, s16
	s_addc_u32 s23, s1, 0
	s_lshl_b64 s[0:1], s[18:19], 2
	s_add_u32 s0, s30, s0
	s_addc_u32 s1, s31, s1
	s_lshl_b32 s16, s52, 19
	s_lshl_b32 s17, s25, 17
	v_mul_f32_e32 v0, 0x41000000, v0
	s_or_b32 s16, s17, s16
	v_mul_f32_e32 v106, 0xbfb8aa3b, v0
	v_mul_f32_e32 v112, -2.0, v0
	s_add_u32 s25, s0, s16
	v_cndmask_b32_e64 v36, v20, 0, s[4:5]
	s_waitcnt vmcnt(8)
	v_cndmask_b32_e64 v43, v27, 0, s[4:5]
	v_cndmask_b32_e64 v42, v26, 0, s[4:5]
	v_cndmask_b32_e64 v41, v25, 0, s[4:5]
	v_cndmask_b32_e64 v40, v24, 0, s[4:5]
	s_waitcnt vmcnt(7)
	v_cndmask_b32_e64 v47, v31, 0, s[6:7]
	v_cndmask_b32_e64 v46, v30, 0, s[6:7]
	v_cndmask_b32_e64 v45, v29, 0, s[6:7]
	v_cndmask_b32_e64 v44, v28, 0, s[6:7]
	s_waitcnt vmcnt(6)
	v_cndmask_b32_e64 v51, v51, 0, s[6:7]
	v_cndmask_b32_e64 v50, v50, 0, s[6:7]
	v_cndmask_b32_e64 v49, v49, 0, s[6:7]
	v_cndmask_b32_e64 v48, v48, 0, s[6:7]
	s_waitcnt vmcnt(5)
	v_cndmask_b32_e64 v55, v55, 0, s[6:7]
	v_cndmask_b32_e64 v54, v54, 0, s[6:7]
	v_cndmask_b32_e64 v53, v53, 0, s[6:7]
	v_cndmask_b32_e64 v52, v52, 0, s[6:7]
	s_waitcnt vmcnt(4)
	v_cndmask_b32_e64 v59, v59, 0, s[6:7]
	v_cndmask_b32_e64 v58, v58, 0, s[6:7]
	v_cndmask_b32_e64 v57, v57, 0, s[6:7]
	v_cndmask_b32_e64 v56, v56, 0, s[6:7]
	s_waitcnt vmcnt(3)
	v_cndmask_b32_e64 v63, v63, 0, s[6:7]
	v_cndmask_b32_e64 v62, v62, 0, s[6:7]
	v_cndmask_b32_e64 v61, v61, 0, s[6:7]
	v_cndmask_b32_e64 v60, v60, 0, s[6:7]
	s_waitcnt vmcnt(2)
	v_cndmask_b32_e64 v67, v67, 0, s[6:7]
	v_cndmask_b32_e64 v66, v66, 0, s[6:7]
	v_cndmask_b32_e64 v65, v65, 0, s[6:7]
	v_cndmask_b32_e64 v64, v64, 0, s[6:7]
	s_waitcnt vmcnt(1)
	v_cndmask_b32_e64 v71, v71, 0, s[6:7]
	v_cndmask_b32_e64 v70, v70, 0, s[6:7]
	v_cndmask_b32_e64 v69, v69, 0, s[6:7]
	v_cndmask_b32_e64 v68, v68, 0, s[6:7]
	s_waitcnt vmcnt(0)
	v_cndmask_b32_e64 v75, v11, 0, s[6:7]
	v_cndmask_b32_e64 v74, v10, 0, s[6:7]
	v_cndmask_b32_e64 v73, v9, 0, s[6:7]
	v_cndmask_b32_e64 v72, v8, 0, s[6:7]
	v_mov_b32_e32 v109, v108
	v_mov_b32_e32 v111, v110
	v_mov_b32_e32 v107, v106
	v_mov_b32_e32 v113, v112
	s_addc_u32 s26, s1, 0
	v_mov_b32_e32 v105, 0
	v_add_u32_e32 v200, 0x22000, v121
	ds_write_b32 v200, v202
	v_cmp_gt_u32_e32 vcc, 0x80, v76
	s_and_saveexec_b64 s[16:17], vcc
	ds_write_b32 v200, v203 offset:2048
	s_or_b64 exec, exec, s[16:17]
	s_waitcnt lgkmcnt(0)
	v_bfe_u32 v234, v76, 5, 1
	v_bfe_u32 v235, v116, 3, 1
	v_and_b32_e32 v236, 1, v116
	v_lshlrev_b32_e32 v236, 4, v236
	v_mov_b32_e32 v237, 0x3c00
	v_cmp_eq_u32_e32 vcc, v234, v235
	v_lshlrev_b32_e32 v237, v236, v237
	s_nop 1
	v_cndmask_b32_e32 v237, 0, v237, vcc
	v_bfe_u32 v238, v116, 1, 2
	v_cmp_gt_u32_e64 s[16:17], 16, v116
	v_cmp_eq_u32_e32 vcc, 0, v238
	s_nop 1
	v_cndmask_b32_e32 v239, 0, v237, vcc
	s_nop 0
	v_cndmask_b32_e64 v168, 0, v239, s[16:17]
	v_cndmask_b32_e64 v172, v239, 0, s[16:17]
	v_cmp_eq_u32_e32 vcc, 1, v238
	s_nop 1
	v_cndmask_b32_e32 v239, 0, v237, vcc
	s_nop 0
	v_cndmask_b32_e64 v169, 0, v239, s[16:17]
	v_cndmask_b32_e64 v173, v239, 0, s[16:17]
	v_cmp_eq_u32_e32 vcc, 2, v238
	s_nop 1
	v_cndmask_b32_e32 v239, 0, v237, vcc
	s_nop 0
	v_cndmask_b32_e64 v170, 0, v239, s[16:17]
	v_cndmask_b32_e64 v174, v239, 0, s[16:17]
	v_cmp_eq_u32_e32 vcc, 3, v238
	s_nop 1
	v_cndmask_b32_e32 v239, 0, v237, vcc
	s_nop 0
	v_cndmask_b32_e64 v171, 0, v239, s[16:17]
	v_cndmask_b32_e64 v175, v239, 0, s[16:17]
	v_bfe_u32 v80, v76, 5, 1
	v_lshlrev_b32_e32 v132, 4, v76
	v_and_b32_e32 v132, 0x70, v132
	v_lshlrev_b32_e32 v80, 4, v80
	v_lshlrev_b32_e32 v133, 8, v116
	v_or_b32_e32 v134, 0, v80
	v_xor_b32_e32 v134, v134, v132
	v_add_u32_e32 v134, v133, v134
	v_add_u32_e32 v234, s90, v134
	v_add_u32_e32 v238, 0x22a00, v134
	v_or_b32_e32 v134, 32, v80
	v_xor_b32_e32 v134, v134, v132
	v_add_u32_e32 v134, v133, v134
	v_add_u32_e32 v235, s90, v134
	v_add_u32_e32 v239, 0x22a00, v134
	v_or_b32_e32 v134, 64, v80
	v_xor_b32_e32 v134, v134, v132
	v_add_u32_e32 v134, v133, v134
	v_add_u32_e32 v236, s90, v134
	v_add_u32_e32 v151, 0x22a00, v134
	v_or_b32_e32 v134, 96, v80
	v_xor_b32_e32 v134, v134, v132
	v_add_u32_e32 v134, v133, v134
	v_add_u32_e32 v237, s90, v134
	v_add_u32_e32 v176, 0x22a00, v134
	s_barrier
	s_branch .LBB0_361
